# attention epilogue: the 4 transposed LDS reads of each round issued together (spare registers + v_mov_b64 at the old read sites)
# baseline (speedup 1.0000x reference)
.LBB0_421:
	s_waitcnt vmcnt(24)
	s_waitcnt vmcnt(9)
	ds_write_b128 v205, v[106:109] offset:32768
	s_waitcnt vmcnt(8)
	ds_write_b128 v205, v[110:113] offset:40960
	v_cmp_gt_u32_e32 vcc, 32, v206
	s_and_saveexec_b64 s[4:5], vcc
	ds_write_b32 v208, v181
	s_or_b64 exec, exec, s[4:5]
	s_waitcnt lgkmcnt(0)
	ds_read_b128 v[50:53], v207
	ds_read_b128 v[54:57], v207 offset:32
	s_lshl_b32 s0, s13, 12
	s_add_i32 s0, s0, 0
	s_add_i32 s0, s0, 0x14800
	s_waitcnt lgkmcnt(1)
	v_rcp_f32_e32 v82, v50
	v_rcp_f32_e32 v83, v51
	v_rcp_f32_e32 v84, v52
	v_rcp_f32_e32 v85, v53
	ds_read_b128 v[50:53], v207 offset:64
	s_waitcnt lgkmcnt(1)
	v_rcp_f32_e32 v86, v54
	v_rcp_f32_e32 v87, v55
	v_rcp_f32_e32 v88, v56
	v_rcp_f32_e32 v89, v57
	ds_read_b128 v[54:57], v207 offset:96
	s_waitcnt lgkmcnt(1)
	v_rcp_f32_e32 v90, v50
	v_rcp_f32_e32 v91, v51
	v_and_b32_e32 v50, 31, v0
	v_lshlrev_b32_e32 v51, 4, v0
	v_lshlrev_b32_e32 v50, 2, v50
	v_add_u32_e32 v178, s0, v51
	v_and_b32_e32 v51, 0xfffffe00, v51
	v_rcp_f32_e32 v92, v52
	v_mul_f32_e32 v52, v66, v82
	v_add3_u32 v179, s0, v50, v51
	v_mul_f32_e32 v50, v67, v83
	v_rcp_f32_e32 v93, v53
	ds_write2_b32 v179, v52, v50 offset1:32
	v_mul_f32_e32 v50, v68, v84
	v_mul_f32_e32 v51, v69, v85
	s_waitcnt lgkmcnt(1)
	v_rcp_f32_e32 v94, v54
	v_rcp_f32_e32 v95, v55
	ds_write2_b32 v179, v50, v51 offset0:64 offset1:96
	v_mul_f32_e32 v50, v70, v86
	v_mul_f32_e32 v51, v71, v87
	v_add_u32_e32 v68, 0x400, v179
	v_rcp_f32_e32 v96, v56
	v_rcp_f32_e32 v97, v57
	ds_write2_b32 v68, v50, v51 offset1:32
	v_mul_f32_e32 v50, v72, v88
	v_mul_f32_e32 v51, v73, v89
	ds_write2_b32 v68, v50, v51 offset0:64 offset1:96
	v_mul_f32_e32 v50, v74, v90
	v_mul_f32_e32 v51, v75, v91
	v_add_u32_e32 v69, 0x800, v179
	ds_write2_b32 v69, v50, v51 offset1:32
	v_mul_f32_e32 v50, v76, v92
	v_mul_f32_e32 v51, v77, v93
	ds_write2_b32 v69, v50, v51 offset0:64 offset1:96
	v_mul_f32_e32 v50, v78, v94
	v_mul_f32_e32 v51, v79, v95
	v_add_u32_e32 v70, 0xc00, v179
	ds_write2_b32 v70, v50, v51 offset1:32
	v_mul_f32_e32 v50, v80, v96
	v_mul_f32_e32 v51, v81, v97
	ds_write2_b32 v70, v50, v51 offset0:64 offset1:96
	s_waitcnt lgkmcnt(0)
	v_add_u32_e32 v242, 64, v0
	v_lshl_add_u32 v72, v242, 4, s0
	v_add_u32_e32 v242, 0x80, v0
	v_lshl_add_u32 v75, v242, 4, s0
	v_add_u32_e32 v242, 0xc0, v0
	v_lshl_add_u32 v78, v242, 4, s0
	ds_read_b128 v[62:65], v178
	ds_read_b128 v[230:233], v72
	ds_read_b128 v[234:237], v75
	ds_read_b128 v[238:241], v78
	v_lshlrev_b32_e32 v50, 3, v0
	v_and_b32_e32 v71, 56, v50
	v_lshlrev_b32_e32 v50, 16, v176
	v_and_b32_e32 v51, 0xffff0000, v176
	s_waitcnt lgkmcnt(0)
	v_mul_f32_e32 v50, v62, v50
	v_mul_f32_e32 v51, v63, v51
	v_cvt_pk_bf16_f32 v50, v50, v51
	v_lshlrev_b32_e32 v51, 16, v177
	v_and_b32_e32 v52, 0xffff0000, v177
	v_mul_f32_e32 v51, v64, v51
	v_mul_f32_e32 v52, v65, v52
	v_cvt_pk_bf16_f32 v51, v51, v52
	v_add_u32_e32 v52, 64, v0
	v_lshl_add_u32 v72, v52, 4, s0
	v_mov_b64_e32 v[58:59], v[230:231]
	v_mov_b64_e32 v[60:61], v[232:233]
	v_lshlrev_b32_e32 v53, 8, v0
	v_and_or_b32 v73, v53, s72, v71
	global_store_dwordx2 v73, v[50:51], s[6:7]
	v_lshlrev_b32_e32 v50, 16, v174
	v_and_b32_e32 v51, 0xffff0000, v174
	s_waitcnt lgkmcnt(0)
	v_mul_f32_e32 v50, v58, v50
	v_mul_f32_e32 v51, v59, v51
	v_cvt_pk_bf16_f32 v50, v50, v51
	v_lshlrev_b32_e32 v51, 16, v175
	v_add_u32_e32 v74, 0x80, v0
	v_mul_f32_e32 v51, v60, v51
	v_and_b32_e32 v53, 0xffff0000, v175
	v_lshl_add_u32 v75, v74, 4, s0
	v_mul_f32_e32 v53, v61, v53
	v_cvt_pk_bf16_f32 v51, v51, v53
	v_mov_b64_e32 v[54:55], v[234:235]
	v_mov_b64_e32 v[56:57], v[236:237]
	v_lshlrev_b32_e32 v52, 8, v52
	v_and_or_b32 v76, v52, s72, v71
	global_store_dwordx2 v76, v[50:51], s[6:7]
	v_lshlrev_b32_e32 v50, 16, v172
	v_and_b32_e32 v51, 0xffff0000, v172
	s_waitcnt lgkmcnt(0)
	v_mul_f32_e32 v50, v54, v50
	v_mul_f32_e32 v51, v55, v51
	v_cvt_pk_bf16_f32 v66, v50, v51
	v_lshlrev_b32_e32 v50, 16, v173
	v_and_b32_e32 v51, 0xffff0000, v173
	v_add_u32_e32 v77, 0xc0, v0
	v_mul_f32_e32 v50, v56, v50
	v_mul_f32_e32 v51, v57, v51
	v_lshl_add_u32 v78, v77, 4, s0
	v_cvt_pk_bf16_f32 v67, v50, v51
	v_mov_b64_e32 v[50:51], v[238:239]
	v_mov_b64_e32 v[52:53], v[240:241]
	v_lshlrev_b32_e32 v74, 8, v74
	v_and_or_b32 v74, v74, s72, v71
	global_store_dwordx2 v74, v[66:67], s[6:7]
	v_lshlrev_b32_e32 v66, 16, v170
	v_and_b32_e32 v67, 0xffff0000, v170
	s_waitcnt lgkmcnt(0)
	v_mul_f32_e32 v66, v50, v66
	v_mul_f32_e32 v67, v51, v67
	v_cvt_pk_bf16_f32 v66, v66, v67
	v_lshlrev_b32_e32 v67, 16, v171
	v_lshlrev_b32_e32 v77, 8, v77
	v_mul_f32_e32 v67, v52, v67
	v_and_b32_e32 v79, 0xffff0000, v171
	v_and_or_b32 v71, v77, s72, v71
	v_mul_f32_e32 v79, v53, v79
	v_cvt_pk_bf16_f32 v67, v67, v79
	global_store_dwordx2 v71, v[66:67], s[6:7]
	v_mul_f32_e32 v34, v34, v82
	v_mul_f32_e32 v35, v35, v83
	s_waitcnt lgkmcnt(0)
	ds_write2_b32 v179, v34, v35 offset1:32
	v_mul_f32_e32 v34, v36, v84
	v_mul_f32_e32 v35, v37, v85
	ds_write2_b32 v179, v34, v35 offset0:64 offset1:96
	v_mul_f32_e32 v34, v38, v86
	v_mul_f32_e32 v35, v39, v87
	ds_write2_b32 v68, v34, v35 offset1:32
	v_mul_f32_e32 v34, v40, v88
	v_mul_f32_e32 v35, v41, v89
	ds_write2_b32 v68, v34, v35 offset0:64 offset1:96
	v_mul_f32_e32 v34, v42, v90
	v_mul_f32_e32 v35, v43, v91
	ds_write2_b32 v69, v34, v35 offset1:32
	v_mul_f32_e32 v34, v44, v92
	v_mul_f32_e32 v35, v45, v93
	ds_write2_b32 v69, v34, v35 offset0:64 offset1:96
	v_mul_f32_e32 v34, v46, v94
	v_mul_f32_e32 v35, v47, v95
	ds_write2_b32 v70, v34, v35 offset1:32
	v_mul_f32_e32 v34, v48, v96
	v_mul_f32_e32 v35, v49, v97
	ds_write2_b32 v70, v34, v35 offset0:64 offset1:96
	s_waitcnt lgkmcnt(0)
	ds_read_b128 v[46:49], v178
	ds_read_b128 v[230:233], v72
	ds_read_b128 v[234:237], v75
	ds_read_b128 v[238:241], v78
	v_lshlrev_b32_e32 v34, 16, v168
	v_and_b32_e32 v35, 0xffff0000, v168
	v_and_b32_e32 v36, 0xffff0000, v169
	v_mul_f32_e32 v66, v63, v63
	s_waitcnt lgkmcnt(0)
	v_mul_f32_e32 v34, v46, v34
	v_mul_f32_e32 v35, v47, v35
	v_cvt_pk_bf16_f32 v34, v34, v35
	v_lshlrev_b32_e32 v35, 16, v169
	v_mul_f32_e32 v35, v48, v35
	v_mul_f32_e32 v36, v49, v36
	v_cvt_pk_bf16_f32 v35, v35, v36
	v_mov_b64_e32 v[42:43], v[230:231]
	v_mov_b64_e32 v[44:45], v[232:233]
	global_store_dwordx2 v73, v[34:35], s[6:7] offset:64
	v_lshlrev_b32_e32 v34, 16, v166
	v_and_b32_e32 v35, 0xffff0000, v166
	v_and_b32_e32 v36, 0xffff0000, v167
	s_waitcnt lgkmcnt(0)
	v_mul_f32_e32 v34, v42, v34
	v_mul_f32_e32 v35, v43, v35
	v_cvt_pk_bf16_f32 v34, v34, v35
	v_lshlrev_b32_e32 v35, 16, v167
	v_mul_f32_e32 v35, v44, v35
	v_mul_f32_e32 v36, v45, v36
	v_cvt_pk_bf16_f32 v35, v35, v36
	v_mov_b64_e32 v[38:39], v[234:235]
	v_mov_b64_e32 v[40:41], v[236:237]
	global_store_dwordx2 v76, v[34:35], s[6:7] offset:64
	v_lshlrev_b32_e32 v34, 16, v164
	v_and_b32_e32 v35, 0xffff0000, v164
	v_fmac_f32_e32 v66, v62, v62
	s_waitcnt lgkmcnt(0)
	v_mul_f32_e32 v34, v38, v34
	v_mul_f32_e32 v35, v39, v35
	v_cvt_pk_bf16_f32 v62, v34, v35
	v_lshlrev_b32_e32 v34, 16, v165
	v_and_b32_e32 v35, 0xffff0000, v165
	v_mul_f32_e32 v34, v40, v34
	v_mul_f32_e32 v35, v41, v35
	v_cvt_pk_bf16_f32 v63, v34, v35
	v_mov_b64_e32 v[34:35], v[238:239]
	v_mov_b64_e32 v[36:37], v[240:241]
	global_store_dwordx2 v74, v[62:63], s[6:7] offset:64
	v_lshlrev_b32_e32 v62, 16, v162
	v_and_b32_e32 v63, 0xffff0000, v162
	v_mul_f32_e32 v65, v65, v65
	s_waitcnt lgkmcnt(0)
	v_mul_f32_e32 v62, v34, v62
	v_mul_f32_e32 v63, v35, v63
	v_fmac_f32_e32 v65, v64, v64
	v_cvt_pk_bf16_f32 v62, v62, v63
	v_lshlrev_b32_e32 v63, 16, v163
	v_add_f32_e32 v64, v66, v65
	v_mul_f32_e32 v63, v36, v63
	v_and_b32_e32 v65, 0xffff0000, v163
	v_mul_f32_e32 v65, v37, v65
	v_cvt_pk_bf16_f32 v63, v63, v65
	global_store_dwordx2 v71, v[62:63], s[6:7] offset:64
	v_mul_f32_e32 v18, v18, v82
	v_mul_f32_e32 v19, v19, v83
	s_waitcnt lgkmcnt(0)
	ds_write2_b32 v179, v18, v19 offset1:32
	v_mul_f32_e32 v18, v20, v84
	v_mul_f32_e32 v19, v21, v85
	ds_write2_b32 v179, v18, v19 offset0:64 offset1:96
	v_mul_f32_e32 v18, v22, v86
	v_mul_f32_e32 v19, v23, v87
	ds_write2_b32 v68, v18, v19 offset1:32
	v_mul_f32_e32 v18, v24, v88
	v_mul_f32_e32 v19, v25, v89
	ds_write2_b32 v68, v18, v19 offset0:64 offset1:96
	v_mul_f32_e32 v18, v26, v90
	v_mul_f32_e32 v19, v27, v91
	ds_write2_b32 v69, v18, v19 offset1:32
	v_mul_f32_e32 v18, v28, v92
	v_mul_f32_e32 v19, v29, v93
	ds_write2_b32 v69, v18, v19 offset0:64 offset1:96
	v_mul_f32_e32 v18, v30, v94
	v_mul_f32_e32 v19, v31, v95
	ds_write2_b32 v70, v18, v19 offset1:32
	v_mul_f32_e32 v18, v32, v96
	v_mul_f32_e32 v19, v33, v97
	ds_write2_b32 v70, v18, v19 offset0:64 offset1:96
	s_waitcnt lgkmcnt(0)
	ds_read_b128 v[30:33], v178
	ds_read_b128 v[230:233], v72
	ds_read_b128 v[234:237], v75
	ds_read_b128 v[238:241], v78
	s_waitcnt vmcnt(15)
	v_lshlrev_b32_e32 v18, 16, v128
	v_and_b32_e32 v19, 0xffff0000, v128
	v_and_b32_e32 v22, 0xffff0000, v129
	v_mul_f32_e32 v20, v47, v47
	s_waitcnt lgkmcnt(0)
	v_mul_f32_e32 v18, v30, v18
	v_mul_f32_e32 v19, v31, v19
	v_cvt_pk_bf16_f32 v18, v18, v19
	v_lshlrev_b32_e32 v19, 16, v129
	v_mul_f32_e32 v19, v32, v19
	v_mul_f32_e32 v22, v33, v22
	v_cvt_pk_bf16_f32 v19, v19, v22
	v_mov_b64_e32 v[26:27], v[230:231]
	v_mov_b64_e32 v[28:29], v[232:233]
	global_store_dwordx2 v73, v[18:19], s[6:7] offset:128
	s_waitcnt vmcnt(15)
	v_lshlrev_b32_e32 v18, 16, v126
	v_and_b32_e32 v19, 0xffff0000, v126
	v_mul_f32_e32 v21, v49, v49
	s_waitcnt lgkmcnt(0)
	v_mul_f32_e32 v18, v26, v18
	v_mul_f32_e32 v19, v27, v19
	v_fmac_f32_e32 v20, v46, v46
	v_fmac_f32_e32 v21, v48, v48
	v_cvt_pk_bf16_f32 v18, v18, v19
	v_lshlrev_b32_e32 v19, 16, v127
	v_add_f32_e32 v20, v20, v21
	v_mul_f32_e32 v19, v28, v19
	v_and_b32_e32 v21, 0xffff0000, v127
	v_mul_f32_e32 v21, v29, v21
	v_cvt_pk_bf16_f32 v19, v19, v21
	v_mov_b64_e32 v[22:23], v[234:235]
	v_mov_b64_e32 v[24:25], v[236:237]
	global_store_dwordx2 v76, v[18:19], s[6:7] offset:128
	s_waitcnt vmcnt(15)
	v_lshlrev_b32_e32 v18, 16, v124
	v_and_b32_e32 v19, 0xffff0000, v124
	v_add_f32_e32 v48, v64, v20
	s_waitcnt lgkmcnt(0)
	v_mul_f32_e32 v18, v22, v18
	v_mul_f32_e32 v19, v23, v19
	v_cvt_pk_bf16_f32 v46, v18, v19
	v_lshlrev_b32_e32 v18, 16, v125
	v_and_b32_e32 v19, 0xffff0000, v125
	v_mul_f32_e32 v18, v24, v18
	v_mul_f32_e32 v19, v25, v19
	v_cvt_pk_bf16_f32 v47, v18, v19
	v_mov_b64_e32 v[18:19], v[238:239]
	v_mov_b64_e32 v[20:21], v[240:241]
	v_mul_f32_e32 v49, v31, v31
	v_fmac_f32_e32 v49, v30, v30
	s_waitcnt vmcnt(14)
	v_lshlrev_b32_e32 v30, 16, v122
	v_and_b32_e32 v31, 0xffff0000, v122
	s_waitcnt lgkmcnt(0)
	v_mul_f32_e32 v30, v18, v30
	v_mul_f32_e32 v31, v19, v31
	global_store_dwordx2 v74, v[46:47], s[6:7] offset:128
	v_cvt_pk_bf16_f32 v30, v30, v31
	v_lshlrev_b32_e32 v31, 16, v123
	v_mul_f32_e32 v31, v20, v31
	v_and_b32_e32 v46, 0xffff0000, v123
	v_mul_f32_e32 v46, v21, v46
	v_cvt_pk_bf16_f32 v31, v31, v46
	global_store_dwordx2 v71, v[30:31], s[6:7] offset:128
	v_mul_f32_e32 v2, v2, v82
	v_mul_f32_e32 v3, v3, v83
	s_waitcnt lgkmcnt(0)
	ds_write2_b32 v179, v2, v3 offset1:32
	v_mul_f32_e32 v2, v4, v84
	v_mul_f32_e32 v3, v5, v85
	ds_write2_b32 v179, v2, v3 offset0:64 offset1:96
	v_mul_f32_e32 v2, v6, v86
	v_mul_f32_e32 v3, v7, v87
	ds_write2_b32 v68, v2, v3 offset1:32
	v_mul_f32_e32 v2, v8, v88
	v_mul_f32_e32 v3, v9, v89
	ds_write2_b32 v68, v2, v3 offset0:64 offset1:96
	v_mul_f32_e32 v2, v10, v90
	v_mul_f32_e32 v3, v11, v91
	ds_write2_b32 v69, v2, v3 offset1:32
	v_mul_f32_e32 v2, v12, v92
	v_mul_f32_e32 v3, v13, v93
	ds_write2_b32 v69, v2, v3 offset0:64 offset1:96
	v_mul_f32_e32 v2, v14, v94
	v_mul_f32_e32 v3, v15, v95
	ds_write2_b32 v70, v2, v3 offset1:32
	v_mul_f32_e32 v2, v16, v96
	v_mul_f32_e32 v3, v17, v97
	ds_write2_b32 v70, v2, v3 offset0:64 offset1:96
	s_waitcnt lgkmcnt(0)
	ds_read_b128 v[2:5], v178
	ds_read_b128 v[230:233], v72
	ds_read_b128 v[234:237], v75
	ds_read_b128 v[238:241], v78
	v_mul_f32_e32 v33, v33, v33
	v_fmac_f32_e32 v33, v32, v32
	v_add_f32_e32 v6, v49, v33
	v_add_f32_e32 v16, v48, v6
	s_waitcnt vmcnt(15)
	v_lshlrev_b32_e32 v6, 16, v120
	v_and_b32_e32 v7, 0xffff0000, v120
	s_waitcnt lgkmcnt(0)
	v_mul_f32_e32 v6, v2, v6
	v_mul_f32_e32 v7, v3, v7
	v_cvt_pk_bf16_f32 v6, v6, v7
	v_lshlrev_b32_e32 v7, 16, v121
	v_mul_f32_e32 v7, v4, v7
	v_and_b32_e32 v8, 0xffff0000, v121
	v_mul_f32_e32 v8, v5, v8
	v_cvt_pk_bf16_f32 v7, v7, v8
	v_mov_b64_e32 v[10:11], v[230:231]
	v_mov_b64_e32 v[12:13], v[232:233]
	v_mul_f32_e32 v17, v3, v3
	v_fmac_f32_e32 v17, v2, v2
	s_waitcnt vmcnt(14)
	v_lshlrev_b32_e32 v2, 16, v118
	v_and_b32_e32 v3, 0xffff0000, v118
	s_waitcnt lgkmcnt(0)
	v_mul_f32_e32 v2, v10, v2
	v_mul_f32_e32 v3, v11, v3
	global_store_dwordx2 v73, v[6:7], s[6:7] offset:192
	v_cvt_pk_bf16_f32 v2, v2, v3
	v_lshlrev_b32_e32 v3, 16, v119
	v_and_b32_e32 v6, 0xffff0000, v119
	v_mul_f32_e32 v3, v12, v3
	v_mul_f32_e32 v6, v13, v6
	v_cvt_pk_bf16_f32 v3, v3, v6
	v_mov_b64_e32 v[6:7], v[234:235]
	v_mov_b64_e32 v[8:9], v[236:237]
	global_store_dwordx2 v76, v[2:3], s[6:7] offset:192
	s_waitcnt vmcnt(15)
	v_lshlrev_b32_e32 v2, 16, v116
	v_and_b32_e32 v3, 0xffff0000, v116
	v_mul_f32_e32 v30, v5, v5
	s_waitcnt lgkmcnt(0)
	v_mul_f32_e32 v2, v6, v2
	v_mul_f32_e32 v3, v7, v3
	v_cvt_pk_bf16_f32 v14, v2, v3
	v_lshlrev_b32_e32 v2, 16, v117
	v_and_b32_e32 v3, 0xffff0000, v117
	v_mul_f32_e32 v2, v8, v2
	v_mul_f32_e32 v3, v9, v3
	v_fmac_f32_e32 v30, v4, v4
	v_cvt_pk_bf16_f32 v15, v2, v3
	v_mov_b64_e32 v[2:3], v[238:239]
	v_mov_b64_e32 v[4:5], v[240:241]
	global_store_dwordx2 v74, v[14:15], s[6:7] offset:192
	s_waitcnt vmcnt(15)
	v_lshlrev_b32_e32 v14, 16, v114
	v_and_b32_e32 v15, 0xffff0000, v114
	v_add_f32_e32 v17, v17, v30
	s_waitcnt lgkmcnt(0)
	v_mul_f32_e32 v14, v2, v14
	v_mul_f32_e32 v15, v3, v15
	v_cvt_pk_bf16_f32 v14, v14, v15
	v_lshlrev_b32_e32 v15, 16, v115
	v_add_f32_e32 v30, v16, v17
	v_mul_f32_e32 v15, v4, v15
	v_and_b32_e32 v16, 0xffff0000, v115
	v_mul_f32_e32 v16, v5, v16
	v_cvt_pk_bf16_f32 v15, v15, v16
	global_store_dwordx2 v71, v[14:15], s[6:7] offset:192
	s_waitcnt lgkmcnt(0)
	s_nop 1
	v_add_f32_dpp v14, v30, v30 quad_perm:[1,0,3,2] row_mask:0xf bank_mask:0xf
	s_nop 1
	v_add_f32_dpp v31, v14, v14 quad_perm:[2,3,0,1] row_mask:0xf bank_mask:0xf
	s_nop 1
	v_add_f32_dpp v32, v31, v31 row_half_mirror row_mask:0xf bank_mask:0xf
	s_lshl_b64 s[0:1], s[48:49], 2
	s_add_u32 s4, s18, s0
	s_addc_u32 s5, s19, s1
	v_and_b32_e32 v14, 7, v0
	v_cmp_eq_u32_e32 vcc, 0, v14
	v_ashrrev_i32_e32 v14, 3, v0
	v_ashrrev_i32_e32 v15, 31, v14
	s_and_saveexec_b64 s[6:7], vcc
	s_cbranch_execz .LBB0_425
	v_lshl_add_u64 v[46:47], v[14:15], 2, s[4:5]
	s_waitcnt lgkmcnt(0)
	v_mov_b32_e32 v0, v32
	global_store_dword v[46:47], v0, off
